# phase 4 dealing: blocks <192 whose first item is the longest NSA item hand their short MLA second item to the odd neighbour (runs it as a third item)
# speedup vs baseline: 1.0125x; 1.0125x over previous
; DI unsigned pk2(float a, float b) { f32x2_t v = {a, b}; bf16x2_t r_ = __builtin_convertvector(v, bf16x2_t); return __builtin_bit_cast(unsigned, r_); }
; DI void attn_store(bfu* __restrict__ yrow  , const f32x16 (&o)[2], int hh) {
; #pragma unroll
;   for (int dt = 0; dt < 2; ++dt)
; #pragma unroll
;     for (int g = 0; g < 4; ++g) {
;       u32x2 v = {pk2(o[dt][4 * g], o[dt][4 * g + 1]), pk2(o[dt][4 * g + 2], o[dt][4 * g + 3])};
;       *(u32x2*)(yrow + 32 * dt + 8 * g + 4 * hh) = v;
;     }
; DI void phase_attn2(const Params& p, char* smem) {
;   for (int it = blockIdx.x; it < 1024; it += gridDim.x) {
;     const int j = (it & 511) >> 1;
;     const int idx = (it < 512) ? j : (511 - j);
;     if (it & 1) attn_item<1>(p, idx, smem); else attn_item<3>(p, idx, smem);
;   }
; }
.LBB0_408:
	v_cvt_pk_bf16_f32 v0, v0, v1
	v_cvt_pk_bf16_f32 v1, v2, v3
	global_store_dwordx2 v[16:17], v[0:1], off offset:64
	v_cvt_pk_bf16_f32 v0, v4, v5
	v_cvt_pk_bf16_f32 v1, v6, v7
	global_store_dwordx2 v[16:17], v[0:1], off offset:80
	v_cvt_pk_bf16_f32 v0, v8, v9
	v_cvt_pk_bf16_f32 v1, v10, v11
	global_store_dwordx2 v[16:17], v[0:1], off offset:96
	v_cvt_pk_bf16_f32 v0, v12, v13
	v_cvt_pk_bf16_f32 v1, v14, v15
	v_readlane_b32 s2, v254, 38
	global_store_dwordx2 v[16:17], v[0:1], off offset:112
	v_readlane_b32 s3, v254, 39
	s_load_dword s2, s[2:3], 0x0
	s_waitcnt lgkmcnt(0)
	s_add_i32 s93, s2, s93
	s_and_b32 s2, s93, 0x1ff
	s_cmpk_gt_i32 s93, 0x3ff
	s_cbranch_scc1 .Lp4_tail
	s_cmpk_lt_u32 s2, 0xc0
	s_cbranch_scc0 .LBB0_409
	s_bitcmp0_b32 s2, 0
	s_cbranch_scc1 .LBB0_145
	s_branch .LBB0_409
.Lp4_tail:
	s_cmpk_lt_u32 s2, 0xc0
	s_cbranch_scc0 .LBB0_145
	s_bitcmp1_b32 s93, 0
	s_cbranch_scc0 .LBB0_145
	s_cmpk_ge_i32 s93, 0x600
	s_cbranch_scc1 .LBB0_145
	s_sub_i32 s93, s93, 0x201
